# HGRN step: value-row loads of waves 0,1 split between phases 2 and 3 (per-wave vector-memory balance), first prologue drain dropped
# speedup vs baseline: 1.0001x; 1.0001x over previous
.LBB0_499:
	s_lshl_b32 s14, s4, 1
	s_or_b32 s14, s14, s11
	s_ashr_i32 s15, s14, 31
	s_lshl_b64 s[14:15], s[14:15], 18
	s_add_u32 s11, s72, s14
	s_addc_u32 s14, s73, s15
	s_lshl_b32 s13, s13, 2
	s_add_u32 s11, s11, s13
	s_addc_u32 s13, s14, 0
	s_lshl_b32 s14, s8, 6
	s_add_u32 s14, s11, s14
	s_addc_u32 s15, s13, 0
	v_lshlrev_b32_e32 v0, 2, v58
	v_lshl_add_u64 v[30:31], s[14:15], 0, v[0:1]
	s_and_b64 s[14:15], exec, s[2:3]
	s_mov_b32 s29, 0
	s_cselect_b32 s28, 0, 0x3f000
	v_lshl_add_u64 v[10:11], v[30:31], 0, s[28:29]
	global_load_dwordx4 v[10:13], v[10:11], off
	s_lshr_b32 s13, s10, 7
	s_lshl_b32 s14, s12, 1
	s_lshl_b32 s38, s13, 4
	s_lshl_b64 s[48:49], s[4:5], 24
	s_cmp_le_u32 s14, s13
	s_cselect_b64 s[30:31], -1, 0
	s_lshl_b32 s39, s12, 5
	s_lshl_b32 s28, s12, 6
	s_or_b32 s40, s14, 1
	v_xor_b32_e32 v0, s8, v63
	s_cmp_lt_u32 s14, s13
	v_lshl_add_u32 v70, v0, 4, v90
	v_xor_b32_e32 v0, v16, v63
	v_lshl_or_b32 v16, s12, 4, v50
	s_cselect_b64 s[34:35], -1, 0
	s_lshl_b32 s12, s40, 4
	s_lshl_b32 s47, s40, 5
	s_and_b64 s[50:51], exec, s[2:3]
	s_cselect_b32 s41, s76, s36
	s_cselect_b32 s40, s77, s33
	s_add_u32 s41, s41, s48
	v_mov_b32_e32 v15, v1
	s_waitcnt vmcnt(22)
	v_or_b32_e32 v18, s39, v50
	s_addc_u32 s40, s40, s49
	v_lshl_add_u32 v71, v0, 4, v92
	v_lshl_add_u64 v[32:33], s[6:7], 0, v[14:15]
	v_or_b32_e32 v0, s38, v50
	s_movk_i32 s6, 0x110
	v_mul_u32_u24_e32 v17, 0x110, v16
	v_mad_u32_u24 v114, v16, s37, 0
	v_lshl_or_b32 v16, s8, 4, v50
	v_mul_u32_u24_e32 v19, 0x110, v18
	v_or_b32_e32 v18, s39, v58
	s_add_u32 s20, s41, s20
	v_mul_lo_u32 v15, v0, s6
	v_mul_lo_u32 v16, v16, s37
	v_cmp_gt_u32_e64 s[4:5], v18, v0
	v_cmp_lt_u32_e64 s[6:7], v18, v0
	v_or_b32_e32 v20, 2, v18
	v_or_b32_e32 v18, 3, v18
	s_addc_u32 s40, s40, 0
	v_add_u32_e32 v115, 0, v16
	v_lshl_add_u32 v16, s8, 5, v94
	s_mulk_i32 s8, 0x880
	s_mulk_i32 s9, 0x110
	v_cmp_gt_u32_e64 s[10:11], v18, v0
	v_or_b32_e32 v18, s12, v50
	s_add_u32 s20, s20, s21
	v_add_u32_e32 v116, s8, v89
	v_add_u32_e32 v117, s9, v89
	v_cmp_gt_u32_e64 s[8:9], v20, v0
	v_mul_u32_u24_e32 v20, 0x110, v18
	v_or_b32_e32 v18, s12, v58
	s_addc_u32 s21, s40, 0
	v_cmp_gt_u32_e64 s[12:13], v18, v0
	v_cmp_lt_u32_e64 s[14:15], v18, v0
	v_or_b32_e32 v21, 2, v18
	v_or_b32_e32 v18, 3, v18
	s_add_u32 s20, s20, s39
	v_mul_lo_u32 v14, v0, s37
	v_cmp_gt_u32_e64 s[16:17], v21, v0
	v_cmp_gt_u32_e64 s[18:19], v18, v0
	s_addc_u32 s21, s21, 0
	v_lshlrev_b32_e32 v0, 1, v50
	v_mov_b32_e32 v18, 0
	s_mov_b32 s46, 1
	v_add_u32_e32 v113, v91, v14
	v_lshl_add_u64 v[34:35], s[20:21], 0, v[0:1]
	v_subrev_u32_e32 v0, s39, v106
	s_sub_i32 s48, 0, s25
	v_or_b32_e32 v118, s38, v58
	v_subrev_u32_e32 v119, s38, v104
	v_or_b32_e32 v120, s39, v74
	s_mov_b32 s49, 62
	v_add_u32_e32 v121, v99, v19
	v_add_u32_e32 v122, v99, v20
	v_add_u32_e32 v123, v100, v17
	v_add_u32_e32 v124, v93, v14
	v_add_u32_e32 v125, v16, v96
	v_add_u32_e32 v126, v99, v15
	s_mov_b32 s50, s29
	v_mov_b32_e32 v19, v18
	v_mov_b32_e32 v20, v18
	v_mov_b32_e32 v21, v18
	v_mov_b32_e32 v14, v18
	v_mov_b32_e32 v15, v18
	v_mov_b32_e32 v16, v18
	v_mov_b32_e32 v17, v18
	s_and_b64 s[94:95], s[2:3], exec
	s_cselect_b32 s93, 0, -1
	v_readfirstlane_b32 s54, v26
	v_readfirstlane_b32 s55, v27
	v_readfirstlane_b32 s56, v28
	v_readfirstlane_b32 s57, v29
	v_readfirstlane_b32 s58, v32
	v_readfirstlane_b32 s59, v33
	v_readfirstlane_b32 s60, v34
	v_readfirstlane_b32 s61, v35
	s_lshl_b32 s94, s24, 1
	s_add_i32 s95, s25, 64
	s_sub_i32 s96, 0xfb8, s25
	s_cmp_eq_u32 s93, 0
	s_cselect_b32 s95, s95, s96
	s_mul_i32 s96, s95, s94
	s_add_u32 s54, s54, s96
	s_addc_u32 s55, s55, 0
	s_mul_i32 s96, s95, 0x4800
	s_add_u32 s56, s56, s96
	s_addc_u32 s57, s57, 0
	s_cmp_eq_u32 s93, 0
	s_cselect_b32 s95, 64, 0xf80
	s_mul_i32 s96, s95, 0x4800
	s_add_u32 s58, s58, s96
	s_addc_u32 s59, s59, 0
	s_and_b32 s96, s93, 0xfc0000
	s_add_u32 s60, s60, s96
	s_addc_u32 s61, s61, 0
	s_lshl_b32 s62, s94, 6
	s_xor_b32 s62, s62, s93
	s_sub_i32 s62, s62, s93
	s_xor_b32 s63, s93, 0x120000
	s_sub_i32 s63, s63, s93
	s_xor_b32 s92, s93, 0x40000
	s_sub_i32 s92, s92, s93
	v_lshlrev_b32_e32 v140, 2, v220
	s_mul_i32 s95, s94, 7
	s_and_b32 s95, s95, s93
	v_add_u32_e32 v140, s95, v140
	s_xor_b32 s95, s94, s93
	s_sub_i32 s95, s95, s93
	v_add_u32_e32 v141, s95, v140
	v_add_u32_e32 v142, s95, v141
	v_add_u32_e32 v143, s95, v142
	v_add_u32_e32 v144, s95, v143
	v_add_u32_e32 v145, s95, v144
	v_add_u32_e32 v146, s95, v145
	v_add_u32_e32 v147, s95, v146
	v_lshlrev_b32_e32 v148, 2, v220
	s_and_b32 s95, s93, 0x1f800
	v_add_u32_e32 v148, s95, v148
	s_xor_b32 s95, s93, 0x4800
	s_sub_i32 s95, s95, s93
	v_add_u32_e32 v149, s95, v148
	v_add_u32_e32 v150, s95, v149
	v_add_u32_e32 v151, s95, v150
	v_add_u32_e32 v152, s95, v151
	v_add_u32_e32 v153, s95, v152
	v_add_u32_e32 v154, s95, v153
	v_add_u32_e32 v155, s95, v154
	s_and_b32 s96, s93, 64
	v_xor_b32_e32 v156, s93, v120
	v_add_u32_e32 v156, s96, v156
	v_mul_u32_u24_e32 v156, 0x4800, v156
	v_lshl_add_u32 v156, v50, 2, v156
	v_add_u32_e32 v157, s95, v156
	v_add_u32_e32 v158, s95, v157
	v_add_u32_e32 v159, s95, v158
	v_add_u32_e32 v160, s95, v159
	v_add_u32_e32 v161, s95, v160
	v_add_u32_e32 v162, s95, v161
	v_add_u32_e32 v163, s95, v162
	v_xor_b32_e32 v164, s93, v118
	v_add_u32_e32 v164, s96, v164
	v_lshlrev_b32_e32 v164, 12, v164
	v_lshl_add_u32 v164, v50, 1, v164
	s_xor_b32 s95, s93, 0x1000
	s_sub_i32 s95, s95, s93
	v_add_u32_e32 v165, s95, v164
	v_add_u32_e32 v166, s95, v165
	v_add_u32_e32 v167, s95, v166
	v_add_u32_e32 v222, v114, v81
	v_add_u32_e32 v223, v114, v82
	v_add_u32_e32 v224, v115, v81
	v_add_u32_e32 v225, v115, v82
	v_add_u32_e32 v226, v95, v81
	v_add_u32_e32 v227, v95, v82
	v_add_u32_e32 v228, s28, v113
	v_add_u32_e32 v229, s47, v113
	v_and_b32_e32 v0, 31, v220
	v_lshrrev_b32_e32 v230, 5, v220
	v_lshl_or_b32 v231, v0, 1, v230
	v_mul_u32_u24_e32 v230, 0x110, v230
	v_lshl_add_u32 v230, v0, 3, v230
	s_mul_i32 s95, s25, 0x110
	v_add_u32_e32 v230, s95, v230
	s_lshr_b32 s95, s25, 3
	v_and_b32_e32 v0, 7, v231
	v_xor_b32_e32 v0, s95, v0
	v_mul_u32_u24_e32 v231, 0x120, v231
	v_lshl_add_u32 v231, v0, 4, v231
	v_lshrrev_b32_e32 v0, 5, v220
	s_and_b32 s95, s93, 7
	v_xor_b32_e32 v0, s95, v0
	v_and_b32_e32 v141, 31, v220
	v_lshlrev_b32_e32 v141, 3, v141
	v_mad_u32_u24 v140, v0, s94, v141
	v_mul_u32_u24_e32 v148, 0x4800, v0
	v_add_u32_e32 v148, v148, v141
	s_lshl_b32 s95, s94, 1
	s_xor_b32 s95, s95, s93
	s_sub_i32 s95, s95, s93
	v_add_u32_e32 v141, s95, v140
	v_add_u32_e32 v142, s95, v141
	v_add_u32_e32 v143, s95, v142
	s_xor_b32 s95, s93, 0x9000
	s_sub_i32 s95, s95, s93
	v_add_u32_e32 v149, s95, v148
	v_add_u32_e32 v150, s95, v149
	v_add_u32_e32 v151, s95, v150
	s_nop 0
	s_sub_u32 s96, s54, s62
	s_subb_u32 s97, s55, s93
	s_sub_u32 s98, s56, s63
	s_subb_u32 s99, s57, s93
	global_load_dwordx2 v[40:41], v140, s[96:97]
	global_load_dwordx2 v[48:49], v148, s[98:99]
	global_load_dwordx2 v[42:43], v141, s[96:97]
	global_load_dwordx2 v[64:65], v149, s[98:99]
	global_load_dwordx2 v[44:45], v142, s[96:97]
	global_load_dwordx2 v[66:67], v150, s[98:99]
	global_load_dwordx2 v[46:47], v143, s[96:97]
	global_load_dwordx2 v[68:69], v151, s[98:99]
	global_load_dwordx2 v[232:233], v140, s[54:55]
	global_load_dwordx2 v[240:241], v148, s[56:57]
	global_load_dwordx2 v[234:235], v141, s[54:55]
	global_load_dwordx2 v[242:243], v149, s[56:57]
	global_load_dwordx2 v[236:237], v142, s[54:55]
	global_load_dwordx2 v[244:245], v150, s[56:57]
	global_load_dwordx2 v[238:239], v143, s[54:55]
	global_load_dwordx2 v[246:247], v151, s[56:57]
	s_add_u32 s54, s54, s62
	s_addc_u32 s55, s55, s93
	s_add_u32 s56, s56, s63
	s_addc_u32 s57, s57, s93
	s_andn2_b64 vcc, exec, s[26:27]
	s_cbranch_vccnz .Lhg_setup_done
	global_load_dword v248, v156, s[58:59] offset:2048 nt
	global_load_dword v249, v157, s[58:59] offset:2048 nt
	global_load_dword v252, v158, s[58:59] offset:2048 nt
	global_load_dword v253, v159, s[58:59] offset:2048 nt
	global_load_dword v254, v160, s[58:59] offset:2048 nt
	global_load_dword v255, v161, s[58:59] offset:2048 nt
	global_load_dword v127, v162, s[58:59] offset:2048 nt
	global_load_dword v0, v163, s[58:59] offset:2048 nt
	s_add_u32 s58, s58, s63
	s_addc_u32 s59, s59, s93

.Lhg_p1e_0:
	s_waitcnt lgkmcnt(0)
	s_barrier
	s_andn2_b64 vcc, exec, s[30:31]
	s_cbranch_vccnz .Lhg_v0_0
	s_andn2_b64 vcc, exec, s[34:35]
	s_cbranch_vccnz .Lhg_v1_0
	ds_read_b128 v[168:171], v126
	ds_read_b128 v[184:187], v121 offset:17408
	ds_read_b128 v[200:203], v122 offset:17408
	ds_read_b128 v[128:131], v123
	ds_read_b128 v[172:175], v126 offset:64
	ds_read_b128 v[188:191], v121 offset:17472
	ds_read_b128 v[204:207], v122 offset:17472
	ds_read_b128 v[132:135], v123 offset:64
	ds_read_b128 v[176:179], v126 offset:128
	ds_read_b128 v[192:195], v121 offset:17536
	ds_read_b128 v[208:211], v122 offset:17536
	ds_read_b128 v[136:139], v123 offset:128
	ds_read_b128 v[180:183], v126 offset:192
	ds_read_b128 v[196:199], v121 offset:17600
	ds_read_b128 v[212:215], v122 offset:17600
	ds_read_b128 v[216:219], v123 offset:192
	s_cmpk_ge_i32 s50, 0xf100
	s_cselect_b32 s96, s62, 0
	s_cselect_b32 s97, s63, 0
	s_cselect_b32 s98, s93, 0
	s_and_b64 s[94:95], exec, s[2:3]
	s_cselect_b32 s94, s46, s49
	s_ashr_i32 s95, s94, 31
	s_lshl_b64 s[94:95], s[94:95], 12
	v_lshl_add_u64 v[22:23], v[30:31], 0, s[94:95]
	global_load_dwordx4 v[22:25], v[22:23], off
	global_load_dwordx2 v[40:41], v140, s[54:55]
	global_load_dwordx2 v[48:49], v148, s[56:57]
	v_pk_mul_f32 v[20:21], v[12:13], v[20:21]
	v_pk_mul_f32 v[18:19], v[10:11], v[18:19]
	v_pk_mul_f32 v[12:13], v[12:13], v[16:17]
	v_pk_mul_f32 v[10:11], v[10:11], v[14:15]
	s_add_i32 s49, s49, -1
	s_add_i32 s46, s46, 1
	s_waitcnt lgkmcnt(14)
	v_mfma_f32_16x16x32_bf16 v[36:39], v[184:187], v[168:171], 0
	s_waitcnt lgkmcnt(13)
	v_mfma_f32_16x16x32_bf16 v[26:29], v[200:203], v[168:171], 0
	s_waitcnt lgkmcnt(12)
	v_mfma_f32_16x16x32_bf16 v[32:35], v[168:171], v[128:131], 0
	global_load_dwordx2 v[42:43], v141, s[54:55]
	s_waitcnt lgkmcnt(10)
	v_mfma_f32_16x16x32_bf16 v[36:39], v[188:191], v[172:175], v[36:39]
	s_waitcnt lgkmcnt(9)
	v_mfma_f32_16x16x32_bf16 v[26:29], v[204:207], v[172:175], v[26:29]
	s_waitcnt lgkmcnt(8)
	v_mfma_f32_16x16x32_bf16 v[32:35], v[172:175], v[132:135], v[32:35]
	global_load_dwordx2 v[64:65], v149, s[56:57]
	s_waitcnt lgkmcnt(6)
	v_mfma_f32_16x16x32_bf16 v[36:39], v[192:195], v[176:179], v[36:39]
	s_waitcnt lgkmcnt(5)
	v_mfma_f32_16x16x32_bf16 v[26:29], v[208:211], v[176:179], v[26:29]
	s_waitcnt lgkmcnt(4)
	v_mfma_f32_16x16x32_bf16 v[32:35], v[176:179], v[136:139], v[32:35]
	s_andn2_b64 vcc, exec, s[26:27]
	s_cbranch_vccnz .Lhg_rv0_b0
	global_load_dword v2, v156, s[58:59] offset:2048 nt
	global_load_dword v3, v157, s[58:59] offset:2048 nt
.Lhg_rv0_b0:
	s_waitcnt lgkmcnt(2)
	v_mfma_f32_16x16x32_bf16 v[36:39], v[196:199], v[180:183], v[36:39]
	s_waitcnt lgkmcnt(1)
	v_mfma_f32_16x16x32_bf16 v[26:29], v[212:215], v[180:183], v[26:29]
	s_waitcnt lgkmcnt(0)
	v_mfma_f32_16x16x32_bf16 v[32:35], v[180:183], v[216:219], v[32:35]
	s_andn2_b64 vcc, exec, s[26:27]
	s_cbranch_vccnz .Lhg_rv1_b0
	global_load_dword v4, v158, s[58:59] offset:2048 nt
	global_load_dword v5, v159, s[58:59] offset:2048 nt
.Lhg_rv1_b0:
	s_nop 7
	v_cndmask_b32_e64 v36, v36, 0, s[4:5]
	v_cndmask_b32_e64 v37, 0, v37, s[6:7]
	v_cndmask_b32_e64 v38, v38, 0, s[8:9]
	v_cndmask_b32_e64 v39, v39, 0, s[10:11]
	v_cvt_pk_bf16_f32 v36, v36, v37
	v_cvt_pk_bf16_f32 v37, v38, v39
	ds_write_b64 v228, v[36:37] offset:57856
	v_cndmask_b32_e64 v26, v26, 0, s[12:13]
	v_cndmask_b32_e64 v27, 0, v27, s[14:15]
	v_cndmask_b32_e64 v28, v28, 0, s[16:17]
	v_cndmask_b32_e64 v29, v29, 0, s[18:19]
	v_cvt_pk_bf16_f32 v26, v26, v27
	v_cvt_pk_bf16_f32 v27, v28, v29
	ds_write_b64 v229, v[26:27] offset:57856
	s_branch .Lhg_p3_0
.Lhg_v1_0:
	ds_read_b128 v[168:171], v126
	ds_read_b128 v[184:187], v121 offset:17408
	ds_read_b128 v[128:131], v123
	ds_read_b128 v[172:175], v126 offset:64
	ds_read_b128 v[188:191], v121 offset:17472
	ds_read_b128 v[132:135], v123 offset:64
	ds_read_b128 v[176:179], v126 offset:128
	ds_read_b128 v[192:195], v121 offset:17536
	ds_read_b128 v[136:139], v123 offset:128
	ds_read_b128 v[180:183], v126 offset:192
	ds_read_b128 v[196:199], v121 offset:17600
	ds_read_b128 v[216:219], v123 offset:192
	s_cmpk_ge_i32 s50, 0xf100
	s_cselect_b32 s96, s62, 0
	s_cselect_b32 s97, s63, 0
	s_cselect_b32 s98, s93, 0
	s_and_b64 s[94:95], exec, s[2:3]
	s_cselect_b32 s94, s46, s49
	s_ashr_i32 s95, s94, 31
	s_lshl_b64 s[94:95], s[94:95], 12
	v_lshl_add_u64 v[22:23], v[30:31], 0, s[94:95]
	global_load_dwordx4 v[22:25], v[22:23], off
	global_load_dwordx2 v[40:41], v140, s[54:55]
	global_load_dwordx2 v[48:49], v148, s[56:57]
	v_pk_mul_f32 v[20:21], v[12:13], v[20:21]
	v_pk_mul_f32 v[18:19], v[10:11], v[18:19]
	v_pk_mul_f32 v[12:13], v[12:13], v[16:17]
	v_pk_mul_f32 v[10:11], v[10:11], v[14:15]
	s_add_i32 s49, s49, -1
	s_add_i32 s46, s46, 1
	s_waitcnt lgkmcnt(10)
	v_mfma_f32_16x16x32_bf16 v[36:39], v[184:187], v[168:171], 0
	s_waitcnt lgkmcnt(9)
	v_mfma_f32_16x16x32_bf16 v[32:35], v[168:171], v[128:131], 0
	global_load_dwordx2 v[42:43], v141, s[54:55]
	s_waitcnt lgkmcnt(7)
	v_mfma_f32_16x16x32_bf16 v[36:39], v[188:191], v[172:175], v[36:39]
	s_waitcnt lgkmcnt(6)
	v_mfma_f32_16x16x32_bf16 v[32:35], v[172:175], v[132:135], v[32:35]
	global_load_dwordx2 v[64:65], v149, s[56:57]
	s_waitcnt lgkmcnt(4)
	v_mfma_f32_16x16x32_bf16 v[36:39], v[192:195], v[176:179], v[36:39]
	s_waitcnt lgkmcnt(3)
	v_mfma_f32_16x16x32_bf16 v[32:35], v[176:179], v[136:139], v[32:35]
	s_andn2_b64 vcc, exec, s[26:27]
	s_cbranch_vccnz .Lhg_rv0_a0
	global_load_dword v2, v156, s[58:59] offset:2048 nt
	global_load_dword v3, v157, s[58:59] offset:2048 nt
.Lhg_rv0_a0:
	s_waitcnt lgkmcnt(1)
	v_mfma_f32_16x16x32_bf16 v[36:39], v[196:199], v[180:183], v[36:39]
	s_waitcnt lgkmcnt(0)
	v_mfma_f32_16x16x32_bf16 v[32:35], v[180:183], v[216:219], v[32:35]
	s_andn2_b64 vcc, exec, s[26:27]
	s_cbranch_vccnz .Lhg_rv1_a0
	global_load_dword v4, v158, s[58:59] offset:2048 nt
	global_load_dword v5, v159, s[58:59] offset:2048 nt
.Lhg_rv1_a0:
	s_nop 7
	v_cndmask_b32_e64 v36, v36, 0, s[4:5]
	v_cndmask_b32_e64 v37, 0, v37, s[6:7]
	v_cndmask_b32_e64 v38, v38, 0, s[8:9]
	v_cndmask_b32_e64 v39, v39, 0, s[10:11]
	v_cvt_pk_bf16_f32 v36, v36, v37
	v_cvt_pk_bf16_f32 v37, v38, v39
	ds_write_b64 v228, v[36:37] offset:57856
	v_mov_b32_e32 v26, 0
	v_mov_b32_e32 v27, 0
	ds_write_b64 v229, v[26:27] offset:57856
	s_branch .Lhg_p3_0
.Lhg_v0_0:
	ds_read_b128 v[168:171], v126
	ds_read_b128 v[128:131], v123
	ds_read_b128 v[172:175], v126 offset:64
	ds_read_b128 v[132:135], v123 offset:64
	ds_read_b128 v[176:179], v126 offset:128
	ds_read_b128 v[136:139], v123 offset:128
	ds_read_b128 v[180:183], v126 offset:192
	ds_read_b128 v[216:219], v123 offset:192
	s_cmpk_ge_i32 s50, 0xf100
	s_cselect_b32 s96, s62, 0
	s_cselect_b32 s97, s63, 0
	s_cselect_b32 s98, s93, 0
	s_and_b64 s[94:95], exec, s[2:3]
	s_cselect_b32 s94, s46, s49
	s_ashr_i32 s95, s94, 31
	s_lshl_b64 s[94:95], s[94:95], 12
	v_lshl_add_u64 v[22:23], v[30:31], 0, s[94:95]
	global_load_dwordx4 v[22:25], v[22:23], off
	global_load_dwordx2 v[40:41], v140, s[54:55]
	global_load_dwordx2 v[48:49], v148, s[56:57]
	v_pk_mul_f32 v[20:21], v[12:13], v[20:21]
	v_pk_mul_f32 v[18:19], v[10:11], v[18:19]
	v_pk_mul_f32 v[12:13], v[12:13], v[16:17]
	v_pk_mul_f32 v[10:11], v[10:11], v[14:15]
	s_add_i32 s49, s49, -1
	s_add_i32 s46, s46, 1
	s_waitcnt lgkmcnt(6)
	v_mfma_f32_16x16x32_bf16 v[32:35], v[168:171], v[128:131], 0
	global_load_dwordx2 v[42:43], v141, s[54:55]
	s_waitcnt lgkmcnt(4)
	v_mfma_f32_16x16x32_bf16 v[32:35], v[172:175], v[132:135], v[32:35]
	global_load_dwordx2 v[64:65], v149, s[56:57]
	s_waitcnt lgkmcnt(2)
	v_mfma_f32_16x16x32_bf16 v[32:35], v[176:179], v[136:139], v[32:35]
	s_andn2_b64 vcc, exec, s[26:27]
	s_cbranch_vccnz .Lhg_rv0_n0
	global_load_dword v2, v156, s[58:59] offset:2048 nt
	global_load_dword v3, v157, s[58:59] offset:2048 nt
.Lhg_rv0_n0:
	s_waitcnt lgkmcnt(0)
	v_mfma_f32_16x16x32_bf16 v[32:35], v[180:183], v[216:219], v[32:35]
	s_andn2_b64 vcc, exec, s[26:27]
	s_cbranch_vccnz .Lhg_rv1_n0
	global_load_dword v4, v158, s[58:59] offset:2048 nt
	global_load_dword v5, v159, s[58:59] offset:2048 nt
.Lhg_rv1_n0:
	v_mov_b32_e32 v26, 0
	v_mov_b32_e32 v27, 0
	ds_write_b64 v228, v[26:27] offset:57856
	ds_write_b64 v229, v[26:27] offset:57856
.Lhg_p3_0:
	s_waitcnt lgkmcnt(0)
	s_barrier
	ds_read_b128 v[168:171], v124 offset:57856
	ds_read_b128 v[172:175], v222 offset:53248
	ds_read_b128 v[176:179], v224 offset:34816
	ds_read_b128 v[180:183], v226 offset:53248
	ds_read_b128 v[184:187], v226 offset:55552
	ds_read_b128 v[188:191], v124 offset:57920
	ds_read_b128 v[192:195], v223 offset:53248
	ds_read_b128 v[196:199], v225 offset:34816
	ds_read_b128 v[200:203], v227 offset:53248
	ds_read_b128 v[204:207], v227 offset:55552
	global_load_dwordx2 v[44:45], v142, s[54:55]
	s_waitcnt lgkmcnt(8)
	v_mfma_f32_16x16x32_bf16 v[32:35], v[168:171], v[172:175], v[32:35]
	global_load_dwordx2 v[66:67], v150, s[56:57]
	s_waitcnt lgkmcnt(6)
	v_mfma_f32_16x16x32_bf16 v[18:21], v[176:179], v[180:183], v[18:21]
	global_load_dwordx2 v[46:47], v143, s[54:55]
	s_waitcnt lgkmcnt(5)
	v_mfma_f32_16x16x32_bf16 v[10:13], v[176:179], v[184:187], v[10:13]
	global_load_dwordx2 v[68:69], v151, s[56:57]
	s_waitcnt lgkmcnt(3)
	v_mfma_f32_16x16x32_bf16 v[32:35], v[188:191], v[192:195], v[32:35]
	s_andn2_b64 vcc, exec, s[26:27]
	s_cbranch_vccnz .Lhg_rv2_0
	global_load_dword v6, v160, s[58:59] offset:2048 nt
	global_load_dword v7, v161, s[58:59] offset:2048 nt

.Lhg_p1e_1:
	s_waitcnt lgkmcnt(0)
	s_barrier
	s_andn2_b64 vcc, exec, s[30:31]
	s_cbranch_vccnz .Lhg_v0_1
	s_andn2_b64 vcc, exec, s[34:35]
	s_cbranch_vccnz .Lhg_v1_1
	ds_read_b128 v[168:171], v126
	ds_read_b128 v[184:187], v121 offset:17408
	ds_read_b128 v[200:203], v122 offset:17408
	ds_read_b128 v[128:131], v123
	ds_read_b128 v[172:175], v126 offset:64
	ds_read_b128 v[188:191], v121 offset:17472
	ds_read_b128 v[204:207], v122 offset:17472
	ds_read_b128 v[132:135], v123 offset:64
	ds_read_b128 v[176:179], v126 offset:128
	ds_read_b128 v[192:195], v121 offset:17536
	ds_read_b128 v[208:211], v122 offset:17536
	ds_read_b128 v[136:139], v123 offset:128
	ds_read_b128 v[180:183], v126 offset:192
	ds_read_b128 v[196:199], v121 offset:17600
	ds_read_b128 v[212:215], v122 offset:17600
	ds_read_b128 v[216:219], v123 offset:192
	s_cmpk_ge_i32 s50, 0xf100
	s_cselect_b32 s96, s62, 0
	s_cselect_b32 s97, s63, 0
	s_cselect_b32 s98, s93, 0
	s_and_b64 s[94:95], exec, s[2:3]
	s_cselect_b32 s94, s46, s49
	s_ashr_i32 s95, s94, 31
	s_lshl_b64 s[94:95], s[94:95], 12
	v_lshl_add_u64 v[22:23], v[30:31], 0, s[94:95]
	global_load_dwordx4 v[22:25], v[22:23], off
	global_load_dwordx2 v[232:233], v140, s[54:55]
	global_load_dwordx2 v[240:241], v148, s[56:57]
	v_pk_mul_f32 v[20:21], v[12:13], v[20:21]
	v_pk_mul_f32 v[18:19], v[10:11], v[18:19]
	v_pk_mul_f32 v[12:13], v[12:13], v[16:17]
	v_pk_mul_f32 v[10:11], v[10:11], v[14:15]
	s_add_i32 s49, s49, -1
	s_add_i32 s46, s46, 1
	s_waitcnt lgkmcnt(14)
	v_mfma_f32_16x16x32_bf16 v[36:39], v[184:187], v[168:171], 0
	s_waitcnt lgkmcnt(13)
	v_mfma_f32_16x16x32_bf16 v[26:29], v[200:203], v[168:171], 0
	s_waitcnt lgkmcnt(12)
	v_mfma_f32_16x16x32_bf16 v[32:35], v[168:171], v[128:131], 0
	global_load_dwordx2 v[234:235], v141, s[54:55]
	s_waitcnt lgkmcnt(10)
	v_mfma_f32_16x16x32_bf16 v[36:39], v[188:191], v[172:175], v[36:39]
	s_waitcnt lgkmcnt(9)
	v_mfma_f32_16x16x32_bf16 v[26:29], v[204:207], v[172:175], v[26:29]
	s_waitcnt lgkmcnt(8)
	v_mfma_f32_16x16x32_bf16 v[32:35], v[172:175], v[132:135], v[32:35]
	global_load_dwordx2 v[242:243], v149, s[56:57]
	s_waitcnt lgkmcnt(6)
	v_mfma_f32_16x16x32_bf16 v[36:39], v[192:195], v[176:179], v[36:39]
	s_waitcnt lgkmcnt(5)
	v_mfma_f32_16x16x32_bf16 v[26:29], v[208:211], v[176:179], v[26:29]
	s_waitcnt lgkmcnt(4)
	v_mfma_f32_16x16x32_bf16 v[32:35], v[176:179], v[136:139], v[32:35]
	s_andn2_b64 vcc, exec, s[26:27]
	s_cbranch_vccnz .Lhg_rv0_b1
	global_load_dword v248, v156, s[58:59] offset:2048 nt
	global_load_dword v249, v157, s[58:59] offset:2048 nt
.Lhg_rv0_b1:
	s_waitcnt lgkmcnt(2)
	v_mfma_f32_16x16x32_bf16 v[36:39], v[196:199], v[180:183], v[36:39]
	s_waitcnt lgkmcnt(1)
	v_mfma_f32_16x16x32_bf16 v[26:29], v[212:215], v[180:183], v[26:29]
	s_waitcnt lgkmcnt(0)
	v_mfma_f32_16x16x32_bf16 v[32:35], v[180:183], v[216:219], v[32:35]
	s_andn2_b64 vcc, exec, s[26:27]
	s_cbranch_vccnz .Lhg_rv1_b1
	global_load_dword v252, v158, s[58:59] offset:2048 nt
	global_load_dword v253, v159, s[58:59] offset:2048 nt

.Lhg_v1_1:
	ds_read_b128 v[168:171], v126
	ds_read_b128 v[184:187], v121 offset:17408
	ds_read_b128 v[128:131], v123
	ds_read_b128 v[172:175], v126 offset:64
	ds_read_b128 v[188:191], v121 offset:17472
	ds_read_b128 v[132:135], v123 offset:64
	ds_read_b128 v[176:179], v126 offset:128
	ds_read_b128 v[192:195], v121 offset:17536
	ds_read_b128 v[136:139], v123 offset:128
	ds_read_b128 v[180:183], v126 offset:192
	ds_read_b128 v[196:199], v121 offset:17600
	ds_read_b128 v[216:219], v123 offset:192
	s_cmpk_ge_i32 s50, 0xf100
	s_cselect_b32 s96, s62, 0
	s_cselect_b32 s97, s63, 0
	s_cselect_b32 s98, s93, 0
	s_and_b64 s[94:95], exec, s[2:3]
	s_cselect_b32 s94, s46, s49
	s_ashr_i32 s95, s94, 31
	s_lshl_b64 s[94:95], s[94:95], 12
	v_lshl_add_u64 v[22:23], v[30:31], 0, s[94:95]
	global_load_dwordx4 v[22:25], v[22:23], off
	global_load_dwordx2 v[232:233], v140, s[54:55]
	global_load_dwordx2 v[240:241], v148, s[56:57]
	v_pk_mul_f32 v[20:21], v[12:13], v[20:21]
	v_pk_mul_f32 v[18:19], v[10:11], v[18:19]
	v_pk_mul_f32 v[12:13], v[12:13], v[16:17]
	v_pk_mul_f32 v[10:11], v[10:11], v[14:15]
	s_add_i32 s49, s49, -1
	s_add_i32 s46, s46, 1
	s_waitcnt lgkmcnt(10)
	v_mfma_f32_16x16x32_bf16 v[36:39], v[184:187], v[168:171], 0
	s_waitcnt lgkmcnt(9)
	v_mfma_f32_16x16x32_bf16 v[32:35], v[168:171], v[128:131], 0
	global_load_dwordx2 v[234:235], v141, s[54:55]
	s_waitcnt lgkmcnt(7)
	v_mfma_f32_16x16x32_bf16 v[36:39], v[188:191], v[172:175], v[36:39]
	s_waitcnt lgkmcnt(6)
	v_mfma_f32_16x16x32_bf16 v[32:35], v[172:175], v[132:135], v[32:35]
	global_load_dwordx2 v[242:243], v149, s[56:57]
	s_waitcnt lgkmcnt(4)
	v_mfma_f32_16x16x32_bf16 v[36:39], v[192:195], v[176:179], v[36:39]
	s_waitcnt lgkmcnt(3)
	v_mfma_f32_16x16x32_bf16 v[32:35], v[176:179], v[136:139], v[32:35]
	s_andn2_b64 vcc, exec, s[26:27]
	s_cbranch_vccnz .Lhg_rv0_a1
	global_load_dword v248, v156, s[58:59] offset:2048 nt
	global_load_dword v249, v157, s[58:59] offset:2048 nt
.Lhg_rv0_a1:
	s_waitcnt lgkmcnt(1)
	v_mfma_f32_16x16x32_bf16 v[36:39], v[196:199], v[180:183], v[36:39]
	s_waitcnt lgkmcnt(0)
	v_mfma_f32_16x16x32_bf16 v[32:35], v[180:183], v[216:219], v[32:35]
	s_andn2_b64 vcc, exec, s[26:27]
	s_cbranch_vccnz .Lhg_rv1_a1
	global_load_dword v252, v158, s[58:59] offset:2048 nt
	global_load_dword v253, v159, s[58:59] offset:2048 nt

.Lhg_v0_1:
	ds_read_b128 v[168:171], v126
	ds_read_b128 v[128:131], v123
	ds_read_b128 v[172:175], v126 offset:64
	ds_read_b128 v[132:135], v123 offset:64
	ds_read_b128 v[176:179], v126 offset:128
	ds_read_b128 v[136:139], v123 offset:128
	ds_read_b128 v[180:183], v126 offset:192
	ds_read_b128 v[216:219], v123 offset:192
	s_cmpk_ge_i32 s50, 0xf100
	s_cselect_b32 s96, s62, 0
	s_cselect_b32 s97, s63, 0
	s_cselect_b32 s98, s93, 0
	s_and_b64 s[94:95], exec, s[2:3]
	s_cselect_b32 s94, s46, s49
	s_ashr_i32 s95, s94, 31
	s_lshl_b64 s[94:95], s[94:95], 12
	v_lshl_add_u64 v[22:23], v[30:31], 0, s[94:95]
	global_load_dwordx4 v[22:25], v[22:23], off
	global_load_dwordx2 v[232:233], v140, s[54:55]
	global_load_dwordx2 v[240:241], v148, s[56:57]
	v_pk_mul_f32 v[20:21], v[12:13], v[20:21]
	v_pk_mul_f32 v[18:19], v[10:11], v[18:19]
	v_pk_mul_f32 v[12:13], v[12:13], v[16:17]
	v_pk_mul_f32 v[10:11], v[10:11], v[14:15]
	s_add_i32 s49, s49, -1
	s_add_i32 s46, s46, 1
	s_waitcnt lgkmcnt(6)
	v_mfma_f32_16x16x32_bf16 v[32:35], v[168:171], v[128:131], 0
	global_load_dwordx2 v[234:235], v141, s[54:55]
	s_waitcnt lgkmcnt(4)
	v_mfma_f32_16x16x32_bf16 v[32:35], v[172:175], v[132:135], v[32:35]
	global_load_dwordx2 v[242:243], v149, s[56:57]
	s_waitcnt lgkmcnt(2)
	v_mfma_f32_16x16x32_bf16 v[32:35], v[176:179], v[136:139], v[32:35]
	s_andn2_b64 vcc, exec, s[26:27]
	s_cbranch_vccnz .Lhg_rv0_n1
	global_load_dword v248, v156, s[58:59] offset:2048 nt
	global_load_dword v249, v157, s[58:59] offset:2048 nt
.Lhg_rv0_n1:
	s_waitcnt lgkmcnt(0)
	v_mfma_f32_16x16x32_bf16 v[32:35], v[180:183], v[216:219], v[32:35]
	s_andn2_b64 vcc, exec, s[26:27]
	s_cbranch_vccnz .Lhg_rv1_n1
	global_load_dword v252, v158, s[58:59] offset:2048 nt
	global_load_dword v253, v159, s[58:59] offset:2048 nt

.Lhg_p3_1:
	s_waitcnt lgkmcnt(0)
	s_barrier
	ds_read_b128 v[168:171], v124 offset:57856
	ds_read_b128 v[172:175], v222 offset:53248
	ds_read_b128 v[176:179], v224 offset:34816
	ds_read_b128 v[180:183], v226 offset:53248
	ds_read_b128 v[184:187], v226 offset:55552
	ds_read_b128 v[188:191], v124 offset:57920
	ds_read_b128 v[192:195], v223 offset:53248
	ds_read_b128 v[196:199], v225 offset:34816
	ds_read_b128 v[200:203], v227 offset:53248
	ds_read_b128 v[204:207], v227 offset:55552
	global_load_dwordx2 v[236:237], v142, s[54:55]
	s_waitcnt lgkmcnt(8)
	v_mfma_f32_16x16x32_bf16 v[32:35], v[168:171], v[172:175], v[32:35]
	global_load_dwordx2 v[244:245], v150, s[56:57]
	s_waitcnt lgkmcnt(6)
	v_mfma_f32_16x16x32_bf16 v[18:21], v[176:179], v[180:183], v[18:21]
	global_load_dwordx2 v[238:239], v143, s[54:55]
	s_waitcnt lgkmcnt(5)
	v_mfma_f32_16x16x32_bf16 v[10:13], v[176:179], v[184:187], v[10:13]
	global_load_dwordx2 v[246:247], v151, s[56:57]
	s_waitcnt lgkmcnt(3)
	v_mfma_f32_16x16x32_bf16 v[32:35], v[188:191], v[192:195], v[32:35]
	s_andn2_b64 vcc, exec, s[26:27]
	s_cbranch_vccnz .Lhg_rv2_1
	global_load_dword v254, v160, s[58:59] offset:2048 nt
	global_load_dword v255, v161, s[58:59] offset:2048 nt
